# lru_s3: de-serialized 80 ushort loads (hoisted, distinct dest regs, single wait)
# speedup vs baseline: 1.0184x; 1.0184x over previous
; #define LAS __attribute__((address_space(3)))
; __device__ __forceinline__ float bf2f(bf16_t b) { return __uint_as_float(((unsigned)b) << 16); }
; __device__ __forceinline__ int opaque_tid() { int t = threadIdx.x; asm volatile("" : "+v"(t)); return t; }
; #define p (*kparams())
; __device__ __forceinline__ void lru_s3_item(CParams& p, int item, LAS unsigned char* lds) {
;     const int cidx = item >> 3, kb = item & 7, b = cidx / NCHK, c = cidx % NCHK;
;     const int tid = opaque_tid(), j = tid & 63, tq = tid >> 6, ch = kb * 64 + j;
;     LAS float* AG = (LAS float*)lds;
;     const bf16_t* P = (const bf16_t*)(p.ws + R_PMIX); const bf16_t* LA = (const bf16_t*)(p.ws + R_LA); const bf16_t* BB = (const bf16_t*)(p.ws + R_BB);
;     bf16_t* Z = (bf16_t*)(p.ws + OFF_Z);
;     float av[2][16], bv[2][16];
;     size_t ro[16];
; #pragma unroll
;     for (int tt = 0; tt < 16; ++tt) ro[tt] = (size_t)row_bci(b, c, 16 * tq + tt);
; #pragma unroll
;     for (int dir = 0; dir < 2; ++dir)
; #pragma unroll
;         for (int tt = 0; tt < 16; ++tt) { const size_t o = (size_t)dir * MP * W + ro[tt] * W + ch; av[dir][tt] = bf2f(LA[o]); bv[dir][tt] = bf2f(BB[o]); }
.LBB0_755:
	s_mov_b64 s[4:5], s[0:1]
	s_ashr_i32 s28, s11, 3
	s_load_dwordx2 s[4:5], s[4:5], 0xe8
	s_mul_hi_i32 s10, s28, 0x7e07e07f
	s_lshr_b32 s14, s10, 31
	s_ashr_i32 s10, s10, 5
	s_add_i32 s14, s10, s14
	s_mul_i32 s36, s14, 0x41
	s_sub_i32 s39, s28, s36
	v_mov_b32_e32 v0, v206
	s_and_b32 s10, s9, 0x1c0
	s_waitcnt lgkmcnt(0)
	s_add_u32 s30, s4, 0x2db02000
	v_and_b32_e32 v93, 63, v0
	v_or_b32_e32 v82, s10, v93
	s_addc_u32 s31, s5, 0
	s_lshl_b32 s15, s14, 13
	s_lshl_b32 s10, s39, 7
	s_add_i32 s15, s15, s10
	s_lshl_b32 s14, s14, 7
	s_addk_i32 s15, 0xff80
	s_addk_i32 s14, 0x4000
	v_ashrrev_i32_e32 v85, 6, v0
	s_cmp_eq_u32 s39, 0
	v_lshlrev_b32_e32 v84, 4, v85
	s_cselect_b32 s14, s14, s15
	v_add_u32_e32 v32, s14, v84
	v_ashrrev_i32_e32 v33, 31, v32
	v_lshlrev_b64 v[34:35], 9, v[32:33]
	s_add_u32 s40, s4, 0x2ba82000
	v_or_b32_e32 v36, v34, v82
	v_mov_b32_e32 v37, v35
	s_addc_u32 s41, s5, 0
	v_lshlrev_b64 v[36:37], 1, v[36:37]
	v_lshl_add_u64 v[38:39], s[40:41], 0, v[36:37]
	global_load_ushort v120, v[38:39], off
	v_lshl_add_u64 v[36:37], s[30:31], 0, v[36:37]
	v_or_b32_e32 v30, 1, v32
	v_ashrrev_i32_e32 v31, 31, v30
	v_or_b32_e32 v28, 2, v32
	v_ashrrev_i32_e32 v29, 31, v28
	v_or_b32_e32 v26, 3, v32
	v_ashrrev_i32_e32 v27, 31, v26
	v_or_b32_e32 v24, 4, v32
	v_ashrrev_i32_e32 v25, 31, v24
	v_or_b32_e32 v22, 5, v32
	v_ashrrev_i32_e32 v23, 31, v22
	v_or_b32_e32 v20, 6, v32
	v_ashrrev_i32_e32 v21, 31, v20
	v_or_b32_e32 v18, 7, v32
	v_ashrrev_i32_e32 v19, 31, v18
	v_or_b32_e32 v16, 8, v32
	v_ashrrev_i32_e32 v17, 31, v16
	v_or_b32_e32 v14, 9, v32
	v_ashrrev_i32_e32 v15, 31, v14
	v_or_b32_e32 v12, 10, v32
	v_ashrrev_i32_e32 v13, 31, v12
	v_or_b32_e32 v10, 11, v32
	v_ashrrev_i32_e32 v11, 31, v10
	v_or_b32_e32 v8, 12, v32
	v_ashrrev_i32_e32 v9, 31, v8
	v_or_b32_e32 v6, 13, v32
	v_ashrrev_i32_e32 v7, 31, v6
	v_or_b32_e32 v4, 14, v32
	v_ashrrev_i32_e32 v5, 31, v4
	v_or_b32_e32 v0, 15, v32
	v_ashrrev_i32_e32 v1, 31, v0
	global_load_ushort v121, v[36:37], off
	v_lshlrev_b64 v[36:37], 9, v[30:31]
	v_or_b32_e32 v38, v36, v82
	v_mov_b32_e32 v39, v37
	v_lshlrev_b64 v[38:39], 1, v[38:39]
	v_lshl_add_u64 v[40:41], s[40:41], 0, v[38:39]
	v_lshl_add_u64 v[38:39], s[30:31], 0, v[38:39]
	global_load_ushort v122, v[40:41], off
	global_load_ushort v123, v[38:39], off
	v_lshlrev_b64 v[38:39], 9, v[28:29]
	v_or_b32_e32 v40, v38, v82
	v_mov_b32_e32 v41, v39
	v_lshlrev_b64 v[40:41], 1, v[40:41]
	v_lshl_add_u64 v[42:43], s[40:41], 0, v[40:41]
	v_lshl_add_u64 v[40:41], s[30:31], 0, v[40:41]
	global_load_ushort v124, v[42:43], off
	global_load_ushort v125, v[40:41], off
	v_lshlrev_b64 v[40:41], 9, v[26:27]
	v_or_b32_e32 v42, v40, v82
	v_mov_b32_e32 v43, v41
	v_lshlrev_b64 v[42:43], 1, v[42:43]
	v_lshl_add_u64 v[44:45], s[40:41], 0, v[42:43]
	v_lshl_add_u64 v[42:43], s[30:31], 0, v[42:43]
	global_load_ushort v126, v[44:45], off
	global_load_ushort v127, v[42:43], off
	v_lshlrev_b64 v[42:43], 9, v[24:25]
	v_or_b32_e32 v44, v42, v82
	v_mov_b32_e32 v45, v43
	v_lshlrev_b64 v[44:45], 1, v[44:45]
	v_lshl_add_u64 v[46:47], s[40:41], 0, v[44:45]
	v_lshl_add_u64 v[44:45], s[30:31], 0, v[44:45]
	global_load_ushort v128, v[46:47], off
	global_load_ushort v129, v[44:45], off
	v_lshlrev_b64 v[44:45], 9, v[22:23]
	v_or_b32_e32 v46, v44, v82
	v_mov_b32_e32 v47, v45
	v_lshlrev_b64 v[46:47], 1, v[46:47]
	v_lshl_add_u64 v[48:49], s[40:41], 0, v[46:47]
	v_lshl_add_u64 v[46:47], s[30:31], 0, v[46:47]
	global_load_ushort v130, v[48:49], off
	global_load_ushort v131, v[46:47], off
	v_lshlrev_b64 v[46:47], 9, v[20:21]
	v_or_b32_e32 v48, v46, v82
	v_mov_b32_e32 v49, v47
	v_lshlrev_b64 v[48:49], 1, v[48:49]
	v_lshl_add_u64 v[50:51], s[40:41], 0, v[48:49]
	v_lshl_add_u64 v[48:49], s[30:31], 0, v[48:49]
	global_load_ushort v132, v[50:51], off
	global_load_ushort v133, v[48:49], off
	v_lshlrev_b64 v[48:49], 9, v[18:19]
	v_or_b32_e32 v50, v48, v82
	v_mov_b32_e32 v51, v49
	v_lshlrev_b64 v[50:51], 1, v[50:51]
	v_lshl_add_u64 v[52:53], s[40:41], 0, v[50:51]
	v_lshl_add_u64 v[50:51], s[30:31], 0, v[50:51]
	global_load_ushort v134, v[52:53], off
	global_load_ushort v135, v[50:51], off
	v_lshlrev_b64 v[50:51], 9, v[16:17]
	v_or_b32_e32 v52, v50, v82
	v_mov_b32_e32 v53, v51
	v_lshlrev_b64 v[52:53], 1, v[52:53]
	v_lshl_add_u64 v[54:55], s[40:41], 0, v[52:53]
	v_lshl_add_u64 v[52:53], s[30:31], 0, v[52:53]
	global_load_ushort v136, v[54:55], off
	global_load_ushort v137, v[52:53], off
	v_lshlrev_b64 v[52:53], 9, v[14:15]
	v_or_b32_e32 v54, v52, v82
	v_mov_b32_e32 v55, v53
	v_lshlrev_b64 v[54:55], 1, v[54:55]
	v_lshl_add_u64 v[56:57], s[40:41], 0, v[54:55]
	v_lshl_add_u64 v[54:55], s[30:31], 0, v[54:55]
	global_load_ushort v138, v[56:57], off
	global_load_ushort v139, v[54:55], off
	v_lshlrev_b64 v[54:55], 9, v[12:13]
	v_or_b32_e32 v56, v54, v82
	v_mov_b32_e32 v57, v55
	v_lshlrev_b64 v[56:57], 1, v[56:57]
	v_lshl_add_u64 v[58:59], s[40:41], 0, v[56:57]
	v_lshl_add_u64 v[56:57], s[30:31], 0, v[56:57]
	global_load_ushort v140, v[58:59], off
	global_load_ushort v141, v[56:57], off
	v_lshlrev_b64 v[56:57], 9, v[10:11]
	v_or_b32_e32 v58, v56, v82
	v_mov_b32_e32 v59, v57
	v_lshlrev_b64 v[58:59], 1, v[58:59]
	v_lshl_add_u64 v[60:61], s[40:41], 0, v[58:59]
	v_lshl_add_u64 v[58:59], s[30:31], 0, v[58:59]
	global_load_ushort v142, v[60:61], off
	global_load_ushort v143, v[58:59], off
	v_lshlrev_b64 v[58:59], 9, v[8:9]
	v_or_b32_e32 v60, v58, v82
	v_mov_b32_e32 v61, v59
	v_lshlrev_b64 v[60:61], 1, v[60:61]
	v_lshl_add_u64 v[62:63], s[40:41], 0, v[60:61]
	v_lshl_add_u64 v[60:61], s[30:31], 0, v[60:61]
	global_load_ushort v144, v[62:63], off
	global_load_ushort v145, v[60:61], off
	v_lshlrev_b64 v[60:61], 9, v[6:7]
; __device__ __forceinline__ float bf2f(bf16_t b) { return __uint_as_float(((unsigned)b) << 16); }
; __device__ __forceinline__ unsigned f2bf(float f) { return pk2(f, 0.f) & 0xffffu; }
; __device__ __forceinline__ float gelu_tanh(float x) { return 0.5f * x * (1.0f + tanhf(0.7978845608028654f * (x + 0.044715f * x * x * x))); }
; __device__ __forceinline__ void lru_s3_item(CParams& p, int item, LAS unsigned char* lds) {
;     ...
;     for (int tt = 0; tt < 16; ++tt) ro[tt] = (size_t)row_bci(b, c, 16 * tq + tt);
; #pragma unroll
;     for (int dir = 0; dir < 2; ++dir)
; #pragma unroll
;         for (int tt = 0; tt < 16; ++tt) { const size_t o = (size_t)dir * MP * W + ro[tt] * W + ch; av[dir][tt] = bf2f(LA[o]); bv[dir][tt] = bf2f(BB[o]); }
;     ...
;     for (int tt = 0; tt < 16; ++tt) { const int i = 16 * tq + tt; const bool valid = (c * 128 + i - 112) >= 0;
;         const float ga = bf2f(P[ro[tt] * NMIX + 512 + ch]);
;         Z[ro[tt] * D + ch] = (bf16_t)(valid ? f2bf(hs[tt] * gelu_tanh(ga)) : 0u); }
	v_or_b32_e32 v62, v60, v82
	v_mov_b32_e32 v63, v61
	v_lshlrev_b64 v[62:63], 1, v[62:63]
	v_lshl_add_u64 v[64:65], s[40:41], 0, v[62:63]
	v_lshl_add_u64 v[62:63], s[30:31], 0, v[62:63]
	global_load_ushort v146, v[64:65], off
	global_load_ushort v147, v[62:63], off
	v_lshlrev_b64 v[62:63], 9, v[4:5]
	v_or_b32_e32 v64, v62, v82
	v_mov_b32_e32 v65, v63
	v_lshlrev_b64 v[64:65], 1, v[64:65]
	v_lshl_add_u64 v[66:67], s[40:41], 0, v[64:65]
	v_lshl_add_u64 v[64:65], s[30:31], 0, v[64:65]
	global_load_ushort v148, v[66:67], off
	global_load_ushort v149, v[64:65], off
	v_lshlrev_b64 v[64:65], 9, v[0:1]
	v_or_b32_e32 v66, v64, v82
	v_mov_b32_e32 v67, v65
	v_lshlrev_b64 v[66:67], 1, v[66:67]
	v_lshl_add_u64 v[86:87], s[40:41], 0, v[66:67]
	v_lshl_add_u64 v[66:67], s[30:31], 0, v[66:67]
	global_load_ushort v150, v[86:87], off
	global_load_ushort v151, v[66:67], off
	v_mov_b32_e32 v67, v2
	v_or_b32_e32 v66, 0x820000, v82
	v_lshl_add_u64 v[34:35], v[34:35], 0, v[66:67]
	v_lshlrev_b64 v[86:87], 1, v[34:35]
	v_lshl_add_u64 v[34:35], s[40:41], 0, v[86:87]
	v_lshl_add_u64 v[86:87], s[30:31], 0, v[86:87]
	global_load_ushort v152, v[34:35], off
	v_lshl_add_u64 v[36:37], v[36:37], 0, v[66:67]
	global_load_ushort v153, v[86:87], off
	v_lshlrev_b64 v[36:37], 1, v[36:37]
	v_lshl_add_u64 v[86:87], s[40:41], 0, v[36:37]
	v_lshl_add_u64 v[36:37], s[30:31], 0, v[36:37]
	global_load_ushort v154, v[36:37], off
	global_load_ushort v155, v[86:87], off
	v_lshl_add_u64 v[36:37], v[38:39], 0, v[66:67]
	v_lshlrev_b64 v[38:39], 1, v[36:37]
	v_lshl_add_u64 v[36:37], s[40:41], 0, v[38:39]
	v_lshl_add_u64 v[38:39], s[30:31], 0, v[38:39]
	global_load_ushort v156, v[36:37], off
	global_load_ushort v157, v[38:39], off
	v_lshl_add_u64 v[38:39], v[40:41], 0, v[66:67]
	v_lshlrev_b64 v[38:39], 1, v[38:39]
	v_lshl_add_u64 v[40:41], s[40:41], 0, v[38:39]
	v_lshl_add_u64 v[38:39], s[30:31], 0, v[38:39]
	global_load_ushort v158, v[38:39], off
	global_load_ushort v159, v[40:41], off
	v_lshl_add_u64 v[38:39], v[42:43], 0, v[66:67]
	v_lshlrev_b64 v[38:39], 1, v[38:39]
	v_lshl_add_u64 v[40:41], s[40:41], 0, v[38:39]
	v_lshl_add_u64 v[38:39], s[30:31], 0, v[38:39]
	global_load_ushort v160, v[40:41], off
	global_load_ushort v161, v[38:39], off
	v_lshl_add_u64 v[38:39], v[44:45], 0, v[66:67]
	v_lshlrev_b64 v[38:39], 1, v[38:39]
	v_lshl_add_u64 v[40:41], s[40:41], 0, v[38:39]
	v_lshl_add_u64 v[38:39], s[30:31], 0, v[38:39]
	global_load_ushort v162, v[40:41], off
	s_nop 0
	global_load_ushort v163, v[38:39], off
	v_lshl_add_u64 v[38:39], v[46:47], 0, v[66:67]
	v_lshlrev_b64 v[38:39], 1, v[38:39]
	v_lshl_add_u64 v[40:41], s[40:41], 0, v[38:39]
	v_lshl_add_u64 v[38:39], s[30:31], 0, v[38:39]
	global_load_ushort v164, v[40:41], off
	global_load_ushort v165, v[38:39], off
	v_lshl_add_u64 v[38:39], v[48:49], 0, v[66:67]
	v_lshlrev_b64 v[38:39], 1, v[38:39]
	v_lshl_add_u64 v[40:41], s[40:41], 0, v[38:39]
	v_lshl_add_u64 v[38:39], s[30:31], 0, v[38:39]
	global_load_ushort v172, v[40:41], off
	s_nop 0
	global_load_ushort v173, v[38:39], off
	v_lshl_add_u64 v[38:39], v[50:51], 0, v[66:67]
	v_lshlrev_b64 v[38:39], 1, v[38:39]
	v_lshl_add_u64 v[40:41], s[40:41], 0, v[38:39]
	v_lshl_add_u64 v[38:39], s[30:31], 0, v[38:39]
	global_load_ushort v174, v[40:41], off
	s_nop 0
	global_load_ushort v175, v[38:39], off
	v_lshl_add_u64 v[38:39], v[52:53], 0, v[66:67]
	v_lshlrev_b64 v[38:39], 1, v[38:39]
	v_lshl_add_u64 v[40:41], s[40:41], 0, v[38:39]
	v_lshl_add_u64 v[38:39], s[30:31], 0, v[38:39]
	global_load_ushort v176, v[40:41], off
	s_nop 0
	global_load_ushort v177, v[38:39], off
	v_lshl_add_u64 v[38:39], v[54:55], 0, v[66:67]
	v_lshlrev_b64 v[38:39], 1, v[38:39]
	v_lshl_add_u64 v[40:41], s[40:41], 0, v[38:39]
	v_lshl_add_u64 v[38:39], s[30:31], 0, v[38:39]
	global_load_ushort v178, v[40:41], off
	s_nop 0
	global_load_ushort v179, v[38:39], off
	v_lshl_add_u64 v[38:39], v[56:57], 0, v[66:67]
	v_lshlrev_b64 v[38:39], 1, v[38:39]
	v_lshl_add_u64 v[40:41], s[40:41], 0, v[38:39]
	v_lshl_add_u64 v[38:39], s[30:31], 0, v[38:39]
	global_load_ushort v180, v[40:41], off
	global_load_ushort v181, v[38:39], off
	v_lshl_add_u64 v[38:39], v[58:59], 0, v[66:67]
	v_lshlrev_b64 v[38:39], 1, v[38:39]
	v_lshl_add_u64 v[40:41], s[40:41], 0, v[38:39]
	v_lshl_add_u64 v[38:39], s[30:31], 0, v[38:39]
	global_load_ushort v182, v[40:41], off
	s_nop 0
	global_load_ushort v183, v[38:39], off
	v_lshl_add_u64 v[38:39], v[60:61], 0, v[66:67]
	v_lshlrev_b64 v[38:39], 1, v[38:39]
	v_lshl_add_u64 v[48:49], s[40:41], 0, v[38:39]
	v_lshl_add_u64 v[38:39], s[30:31], 0, v[38:39]
	global_load_ushort v184, v[48:49], off
	s_nop 0
	global_load_ushort v185, v[38:39], off
	v_lshl_add_u64 v[48:49], v[62:63], 0, v[66:67]
	v_lshlrev_b64 v[48:49], 1, v[48:49]
	v_lshl_add_u64 v[50:51], s[40:41], 0, v[48:49]
	v_lshl_add_u64 v[48:49], s[30:31], 0, v[48:49]
	global_load_ushort v186, v[50:51], off
	global_load_ushort v187, v[48:49], off
	v_lshl_add_u64 v[48:49], v[64:65], 0, v[66:67]
	v_lshlrev_b64 v[48:49], 1, v[48:49]
	v_lshl_add_u64 v[50:51], s[40:41], 0, v[48:49]
	global_load_ushort v188, v[50:51], off
	v_lshl_add_u64 v[48:49], s[30:31], 0, v[48:49]
	global_load_ushort v189, v[48:49], off
	v_lshlrev_b32_e32 v222, 1, v82
	v_add_u32_e32 v222, 0x19602400, v222
	v_mov_b32_e32 v223, 0x3800
	v_mad_u32_u24 v224, v32, v223, v222
	global_load_ushort v190, v224, s[4:5]
	v_mad_u32_u24 v225, v30, v223, v222
	global_load_ushort v191, v225, s[4:5]
	v_mad_u32_u24 v224, v28, v223, v222
	global_load_ushort v192, v224, s[4:5]
	v_mad_u32_u24 v225, v26, v223, v222
	global_load_ushort v193, v225, s[4:5]
	v_mad_u32_u24 v224, v24, v223, v222
	global_load_ushort v194, v224, s[4:5]
	v_mad_u32_u24 v225, v22, v223, v222
	global_load_ushort v195, v225, s[4:5]
	v_mad_u32_u24 v224, v20, v223, v222
	global_load_ushort v196, v224, s[4:5]
	v_mad_u32_u24 v225, v18, v223, v222
	global_load_ushort v197, v225, s[4:5]
	v_mad_u32_u24 v224, v16, v223, v222
	global_load_ushort v198, v224, s[4:5]
	v_mad_u32_u24 v225, v14, v223, v222
	global_load_ushort v199, v225, s[4:5]
	v_mad_u32_u24 v224, v12, v223, v222
	global_load_ushort v200, v224, s[4:5]
	v_mad_u32_u24 v225, v10, v223, v222
	global_load_ushort v201, v225, s[4:5]
	v_mad_u32_u24 v224, v8, v223, v222
	global_load_ushort v202, v224, s[4:5]
	v_mad_u32_u24 v225, v6, v223, v222
	global_load_ushort v203, v225, s[4:5]
	v_mad_u32_u24 v224, v4, v223, v222
	global_load_ushort v204, v224, s[4:5]
	v_mad_u32_u24 v225, v0, v223, v222
	global_load_ushort v205, v225, s[4:5]
	s_waitcnt vmcnt(0)
; __device__ __forceinline__ float bf2f(bf16_t b) { return __uint_as_float(((unsigned)b) << 16); }
; #define p (*kparams())
; __device__ __forceinline__ void lru_s3_item(CParams& p, int item, LAS unsigned char* lds) {
;     ...
;         for (int tt = 0; tt < 16; ++tt) { const size_t o = (size_t)dir * MP * W + ro[tt] * W + ch; av[dir][tt] = bf2f(LA[o]); bv[dir][tt] = bf2f(BB[o]); }
;     __syncthreads();
; #pragma unroll
;     for (int dir = 0; dir < 2; ++dir) { float Aq = 1.f, Bq = 0.f;
; #pragma unroll
;         for (int s = 0; s < 16; ++s) { const int tt = dir ? 15 - s : s; const float a = __expf(av[dir][tt]); av[dir][tt] = a; Bq = a * Bq + bv[dir][tt]; Aq *= a; }
;         AG[((tq * 2 + dir) * 2 + 0) * 64 + j] = Aq; AG[((tq * 2 + dir) * 2 + 1) * 64 + j] = Bq; }
;     __syncthreads();
;     float hs[16];
; #pragma unroll
;     for (int dir = 0; dir < 2; ++dir) {
;         float h = ((const float*)(p.ws + R_CR))[(size_t)((dir * 2 + b) * NCHK + c) * W + ch];
;         for (int s = 0; s < 7; ++s) { const int q = dir ? 7 - s : s; const bool use = dir ? (q > tq) : (q < tq);
;             const float a = AG[((q * 2 + dir) * 2 + 0) * 64 + j], bq = AG[((q * 2 + dir) * 2 + 1) * 64 + j]; if (use) h = a * h + bq; }
	s_mov_b64 s[14:15], 0x3a1ee000
	s_ashr_i32 s29, s28, 31
	v_cmp_lt_i32_e32 vcc, 0, v85
	v_lshlrev_b32_e32 v94, 16, v120
	v_lshlrev_b32_e32 v83, 16, v121
	v_lshlrev_b32_e32 v95, 16, v122
	v_lshlrev_b32_e32 v81, 16, v123
	v_lshlrev_b32_e32 v96, 16, v124
	v_lshlrev_b32_e32 v80, 16, v125
	v_lshlrev_b32_e32 v97, 16, v126
	v_lshlrev_b32_e32 v79, 16, v127
	v_lshlrev_b32_e32 v98, 16, v128
	v_lshlrev_b32_e32 v78, 16, v129
	v_lshlrev_b32_e32 v99, 16, v130
	v_lshlrev_b32_e32 v77, 16, v131
	v_lshlrev_b32_e32 v100, 16, v132
	v_lshlrev_b32_e32 v76, 16, v133
	v_lshlrev_b32_e32 v101, 16, v134
	v_lshlrev_b32_e32 v75, 16, v135
	v_lshlrev_b32_e32 v102, 16, v136
	v_lshlrev_b32_e32 v74, 16, v137
	v_lshlrev_b32_e32 v103, 16, v138
	v_lshlrev_b32_e32 v73, 16, v139
	v_lshlrev_b32_e32 v104, 16, v140
	v_lshlrev_b32_e32 v72, 16, v141
	v_lshlrev_b32_e32 v105, 16, v142
	v_lshlrev_b32_e32 v71, 16, v143
	v_lshlrev_b32_e32 v107, 16, v144
	v_lshlrev_b32_e32 v70, 16, v145
	v_lshlrev_b32_e32 v108, 16, v146
	v_lshlrev_b32_e32 v69, 16, v147
	v_lshlrev_b32_e32 v109, 16, v148
	v_lshlrev_b32_e32 v3, 16, v149
	v_lshlrev_b32_e32 v111, 16, v150
	v_lshlrev_b32_e32 v68, 16, v151
	v_lshlrev_b32_e32 v34, 16, v152
	v_mul_f32_e32 v34, 0x3fb8aa3b, v34
	v_lshlrev_b32_e32 v92, 16, v153
	v_lshlrev_b32_e32 v91, 16, v154
	v_lshlrev_b32_e32 v35, 16, v155
	v_mul_f32_e32 v35, 0x3fb8aa3b, v35
	v_lshlrev_b32_e32 v36, 16, v156
	v_mul_f32_e32 v36, 0x3fb8aa3b, v36
	v_exp_f32_e32 v36, v36
	v_lshlrev_b32_e32 v90, 16, v157
	v_lshlrev_b32_e32 v89, 16, v158
	v_lshlrev_b32_e32 v37, 16, v159
	v_mul_f32_e32 v37, 0x3fb8aa3b, v37
	v_exp_f32_e32 v37, v37
	v_lshlrev_b32_e32 v106, 16, v160
	v_lshlrev_b32_e32 v88, 16, v161
	v_lshlrev_b32_e32 v110, 16, v162
	v_lshlrev_b32_e32 v87, 16, v163
	v_mul_f32_e32 v46, 0x3fb8aa3b, v94
	v_lshlrev_b32_e32 v112, 16, v164
	v_lshlrev_b32_e32 v86, 16, v165
	v_lshlrev_b32_e32 v113, 16, v172
	v_lshlrev_b32_e32 v47, 16, v173
	v_lshlrev_b32_e32 v114, 16, v174
	v_lshlrev_b32_e32 v45, 16, v175
	v_lshlrev_b32_e32 v115, 16, v176
	v_lshlrev_b32_e32 v44, 16, v177
	v_lshlrev_b32_e32 v55, 16, v178
	v_mul_f32_e32 v55, 0x3fb8aa3b, v55
	v_lshlrev_b32_e32 v43, 16, v179
	v_exp_f32_e32 v55, v55
	v_lshlrev_b32_e32 v116, 16, v180
	v_lshlrev_b32_e32 v42, 16, v181
	v_lshlrev_b32_e32 v117, 16, v182
	v_lshlrev_b32_e32 v40, 16, v183
	v_lshl_add_u32 v63, v93, 2, 0
	v_lshlrev_b32_e32 v118, 16, v184
	v_lshlrev_b32_e32 v39, 16, v185
	v_lshlrev_b32_e32 v119, 16, v186
	v_exp_f32_e32 v64, v46
	v_lshl_add_u32 v66, v85, 10, v63
	v_fma_f32 v46, 0, v64, v83
	v_lshlrev_b32_e32 v38, 16, v187
	v_lshlrev_b32_e32 v65, 16, v188
	v_mul_f32_e32 v48, 0x3fb8aa3b, v95
	v_exp_f32_e32 v62, v48
	v_mul_f32_e32 v49, 0x3fb8aa3b, v96
	v_exp_f32_e32 v61, v49
	v_mul_f32_e32 v49, 0x3fb8aa3b, v97
	v_exp_f32_e32 v60, v49
	v_mul_f32_e32 v49, 0x3fb8aa3b, v98
	v_exp_f32_e32 v59, v49
	v_mul_f32_e32 v49, 0x3fb8aa3b, v99
	v_mul_f32_e32 v48, v64, v62
	v_exp_f32_e32 v58, v49
	v_mul_f32_e32 v49, 0x3fb8aa3b, v100
	v_mul_f32_e32 v48, v48, v61
	v_exp_f32_e32 v57, v49
	v_mul_f32_e32 v49, 0x3fb8aa3b, v101
	v_mul_f32_e32 v48, v48, v60
	v_exp_f32_e32 v56, v49
	v_mul_f32_e32 v49, 0x3fb8aa3b, v102
	v_mul_f32_e32 v48, v48, v59
	v_exp_f32_e32 v54, v49
	v_mul_f32_e32 v49, 0x3fb8aa3b, v103
	v_fma_f32 v46, v46, v62, v81
	v_mul_f32_e32 v48, v48, v58
	v_exp_f32_e32 v53, v49
	v_mul_f32_e32 v49, 0x3fb8aa3b, v104
	v_fma_f32 v46, v46, v61, v80
	v_mul_f32_e32 v48, v48, v57
	v_exp_f32_e32 v52, v49
	v_mul_f32_e32 v49, 0x3fb8aa3b, v105
	v_fma_f32 v46, v46, v60, v79
	v_mul_f32_e32 v48, v48, v56
	v_exp_f32_e32 v51, v49
	v_mul_f32_e32 v49, 0x3fb8aa3b, v107
	v_fma_f32 v46, v46, v59, v78
	v_mul_f32_e32 v48, v48, v54
	v_exp_f32_e32 v50, v49
	v_mul_f32_e32 v49, 0x3fb8aa3b, v108
	v_fma_f32 v46, v46, v58, v77
	v_mul_f32_e32 v48, v48, v53
	v_exp_f32_e32 v49, v49
	v_fma_f32 v46, v46, v57, v76
	v_mul_f32_e32 v48, v48, v52
	v_fma_f32 v46, v46, v56, v75
	v_mul_f32_e32 v48, v48, v51
	v_fma_f32 v46, v46, v54, v74
	v_mul_f32_e32 v48, v48, v50
	v_fma_f32 v46, v46, v53, v73
	v_mul_f32_e32 v67, v48, v49
	v_mul_f32_e32 v48, 0x3fb8aa3b, v109
	v_fma_f32 v46, v46, v52, v72
	v_exp_f32_e32 v48, v48
	v_fma_f32 v46, v46, v51, v71
	v_fma_f32 v46, v46, v50, v70
	v_fma_f32 v46, v46, v49, v69
	v_fma_f32 v93, v46, v48, v3
	v_mul_f32_e32 v46, 0x3fb8aa3b, v111
	v_exp_f32_e32 v46, v46
	v_mul_f32_e32 v67, v67, v48
	v_mul_f32_e32 v65, 0x3fb8aa3b, v65
	v_fma_f32 v93, v93, v46, v68
	v_mul_f32_e32 v67, v67, v46
	v_mov_b32_e32 v41, v189
	s_barrier
	ds_write2st64_b32 v66, v67, v93 offset1:1
	v_exp_f32_e32 v65, v65
	v_mul_f32_e32 v67, 0x3fb8aa3b, v119
	v_exp_f32_e32 v67, v67
	s_waitcnt vmcnt(0)
	v_lshlrev_b32_e32 v41, 16, v41
	v_fma_f32 v93, 0, v65, v41
	v_fma_f32 v94, v67, v93, v38
	v_mul_f32_e32 v93, 0x3fb8aa3b, v118
	v_exp_f32_e32 v93, v93
	v_mul_f32_e32 v95, v67, v65
	v_fma_f32 v96, v93, v94, v39
	v_mul_f32_e32 v94, 0x3fb8aa3b, v117
	v_exp_f32_e32 v94, v94
	v_mul_f32_e32 v95, v93, v95
	v_mul_f32_e32 v97, v94, v95
	v_mul_f32_e32 v95, 0x3fb8aa3b, v116
	v_exp_f32_e32 v95, v95
	v_fma_f32 v96, v94, v96, v40
	v_fma_f32 v96, v95, v96, v42
	v_fma_f32 v98, v55, v96, v43
	v_mul_f32_e32 v96, 0x3fb8aa3b, v115
	v_exp_f32_e32 v96, v96
	v_mul_f32_e32 v97, v95, v97
	v_mul_f32_e32 v97, v55, v97
	v_mul_f32_e32 v99, v96, v97
	v_mul_f32_e32 v97, 0x3fb8aa3b, v114
	v_exp_f32_e32 v97, v97
	v_fma_f32 v98, v96, v98, v44
	v_fma_f32 v100, v97, v98, v45
	v_mul_f32_e32 v98, 0x3fb8aa3b, v113
	v_exp_f32_e32 v98, v98
	v_mul_f32_e32 v99, v97, v99
	v_mul_f32_e32 v101, v98, v99
	v_mul_f32_e32 v99, 0x3fb8aa3b, v112
	v_exp_f32_e32 v99, v99
	v_fma_f32 v100, v98, v100, v47
	v_mul_f32_e32 v102, v99, v101
	v_mul_f32_e32 v101, 0x3fb8aa3b, v110
	v_exp_f32_e32 v101, v101
	v_fma_f32 v100, v99, v100, v86
	v_mul_f32_e32 v103, v101, v102
	v_mul_f32_e32 v102, 0x3fb8aa3b, v106
	v_exp_f32_e32 v102, v102
	v_fma_f32 v100, v101, v100, v87
	v_mul_f32_e32 v103, v102, v103
	v_mul_f32_e32 v103, v37, v103
	v_mul_f32_e32 v104, v36, v103
	v_exp_f32_e32 v103, v35
	v_fma_f32 v100, v102, v100, v88
	v_fma_f32 v100, v37, v100, v89
	v_fma_f32 v100, v36, v100, v90
	v_fma_f32 v35, v103, v100, v91
	v_exp_f32_e32 v100, v34
	v_mul_f32_e32 v104, v103, v104
	v_fma_f32 v34, v100, v35, v92
	v_mul_f32_e32 v35, v100, v104
	ds_write2st64_b32 v66, v35, v34 offset0:2 offset1:3
	v_lshlrev_b32_e32 v34, 2, v82
	v_mov_b32_e32 v35, v2
	v_lshl_add_u64 v[34:35], s[4:5], 0, v[34:35]
	v_lshl_add_u64 v[34:35], v[34:35], 0, s[14:15]
	s_lshl_b64 s[14:15], s[28:29], 11
	v_lshl_add_u64 v[104:105], v[34:35], 0, s[14:15]
	s_waitcnt lgkmcnt(0)
	s_barrier
	global_load_dword v66, v[104:105], off
	s_and_saveexec_b64 s[14:15], vcc
	s_cbranch_execz .LBB0_866
	ds_read2st64_b32 v[104:105], v63 offset1:1
	s_waitcnt vmcnt(0) lgkmcnt(0)
	v_fmac_f32_e32 v105, v66, v104
	v_mov_b32_e32 v66, v105
	s_or_b64 exec, exec, s[14:15]
	v_cmp_lt_i32_e32 vcc, 1, v85
	s_and_saveexec_b64 s[14:15], vcc
	s_cbranch_execnz .LBB0_867

; __device__ __forceinline__ float bf2f(bf16_t b) { return __uint_as_float(((unsigned)b) << 16); }
; __device__ __forceinline__ unsigned f2bf(float f) { return pk2(f, 0.f) & 0xffffu; }
; __device__ __forceinline__ float gelu_tanh(float x) { return 0.5f * x * (1.0f + tanhf(0.7978845608028654f * (x + 0.044715f * x * x * x))); }
; __device__ __forceinline__ void lru_s3_item(CParams& p, int item, LAS unsigned char* lds) {
;     ...
;         for (int s = 0; s < 7; ++s) { const int q = dir ? 7 - s : s; const bool use = dir ? (q > tq) : (q < tq);
;             const float a = AG[((q * 2 + dir) * 2 + 0) * 64 + j], bq = AG[((q * 2 + dir) * 2 + 1) * 64 + j]; if (use) h = a * h + bq; }
; #pragma unroll
;         for (int s = 0; s < 16; ++s) { const int tt = dir ? 15 - s : s; h = av[dir][tt] * h + bv[dir][tt]; if (dir == 0) hs[tt] = h; else hs[tt] += h; }
;     }
; #pragma unroll
;     for (int tt = 0; tt < 16; ++tt) { const int i = 16 * tq + tt; const bool valid = (c * 128 + i - 112) >= 0;
;         const float ga = bf2f(P[ro[tt] * NMIX + 512 + ch]);
;         Z[ro[tt] * D + ch] = (bf16_t)(valid ? f2bf(hs[tt] * gelu_tanh(ga)) : 0u); }
.LBB0_771:
	s_or_b64 exec, exec, s[14:15]
	s_waitcnt vmcnt(0)
	v_fmac_f32_e32 v41, v65, v34
	v_fmac_f32_e32 v38, v67, v41
	v_fmac_f32_e32 v39, v93, v38
	v_fmac_f32_e32 v40, v94, v39
	v_fmac_f32_e32 v42, v95, v40
	v_fmac_f32_e32 v43, v55, v42
	v_fmac_f32_e32 v44, v96, v43
	v_fmac_f32_e32 v45, v97, v44
	v_fmac_f32_e32 v47, v98, v45
	v_fmac_f32_e32 v86, v99, v47
	v_fmac_f32_e32 v87, v101, v86
	v_fmac_f32_e32 v88, v102, v87
	v_fmac_f32_e32 v89, v37, v88
	v_fmac_f32_e32 v90, v36, v89
	v_lshlrev_b32_e32 v36, 1, v82
	v_mov_b32_e32 v37, v2
	v_add_u32_e32 v55, s10, v84
	v_lshl_add_u64 v[34:35], s[4:5], 0, v[36:37]
	s_mov_b64 s[14:15], 0x19602400
	v_fmac_f32_e32 v83, v64, v66
	v_fmac_f32_e32 v91, v103, v90
	v_lshl_add_u64 v[34:35], v[34:35], 0, s[14:15]
	v_cmp_lt_i32_e32 vcc, s93, v55
	v_mov_b32_e32 v63, 0
	s_and_saveexec_b64 s[14:15], vcc
	s_cbranch_execz .LBB0_777
	v_mad_i64_i32 v[64:65], s[28:29], v32, s26, v[34:35]
	v_mov_b32_e32 v37, v190
	s_mov_b32 s10, 0x3f200000
	s_waitcnt vmcnt(0)
	v_lshlrev_b32_e32 v37, 16, v37
	v_mul_f32_e32 v63, 0x3d372713, v37
	v_mul_f32_e32 v63, v63, v37
	v_fma_f32 v63, v63, v37, v37
	v_mul_f32_e32 v63, 0x3f4c422a, v63
	v_cmp_nlt_f32_e64 s[28:29], |v63|, s10
	s_and_saveexec_b64 s[30:31], s[28:29]
	s_xor_b64 s[28:29], exec, s[30:31]
	s_cbranch_execz .LBB0_774
	v_add_f32_e64 v64, |v63|, |v63|
	v_mul_f32_e32 v65, 0x3fb8aa3b, v64
	v_rndne_f32_e32 v66, v65
	s_mov_b32 s10, 0x3fb8aa3b
	v_sub_f32_e32 v67, v65, v66
	v_fma_f32 v65, v64, s10, -v65
	v_fmac_f32_e32 v65, 0x32a5705f, v64
	v_add_f32_e32 v65, v67, v65
	v_cvt_i32_f32_e32 v66, v66
	v_exp_f32_e32 v65, v65
	s_mov_b32 s10, 0xc2ce8ed0
	v_cmp_ngt_f32_e32 vcc, s10, v64
	s_mov_b32 s10, 0x42b17218
	v_ldexp_f32 v65, v65, v66
	v_cndmask_b32_e32 v65, 0, v65, vcc
	v_cmp_nlt_f32_e32 vcc, s10, v64
	s_nop 1
	v_cndmask_b32_e32 v64, v213, v65, vcc
	v_add_f32_e32 v64, 1.0, v64
	v_rcp_f32_e32 v64, v64
	s_nop 0
	v_fma_f32 v64, v64, -2.0, 1.0

; __device__ __forceinline__ float bf2f(bf16_t b) { return __uint_as_float(((unsigned)b) << 16); }
; __device__ __forceinline__ unsigned f2bf(float f) { return pk2(f, 0.f) & 0xffffu; }
; __device__ __forceinline__ float gelu_tanh(float x) { return 0.5f * x * (1.0f + tanhf(0.7978845608028654f * (x + 0.044715f * x * x * x))); }
; __device__ __forceinline__ void lru_s3_item(CParams& p, int item, LAS unsigned char* lds) {
;     ...
;         for (int s = 0; s < 16; ++s) { const int tt = dir ? 15 - s : s; h = av[dir][tt] * h + bv[dir][tt]; if (dir == 0) hs[tt] = h; else hs[tt] += h; }
;     }
; #pragma unroll
;     for (int tt = 0; tt < 16; ++tt) { const int i = 16 * tq + tt; const bool valid = (c * 128 + i - 112) >= 0;
;         const float ga = bf2f(P[ro[tt] * NMIX + 512 + ch]);
;         Z[ro[tt] * D + ch] = (bf16_t)(valid ? f2bf(hs[tt] * gelu_tanh(ga)) : 0u); }
.LBB0_777:
	s_or_b64 exec, exec, s[14:15]
	v_mov_b32_e32 v37, v2
	v_lshl_add_u64 v[36:37], s[4:5], 0, v[36:37]
	s_mov_b64 s[4:5], 0xc300000
	v_lshl_add_u64 v[36:37], v[36:37], 0, s[4:5]
	v_lshlrev_b64 v[32:33], 12, v[32:33]
	v_lshl_add_u64 v[32:33], v[36:37], 0, v[32:33]
	s_movk_i32 s4, 0x6e
	v_fmac_f32_e32 v81, v62, v83
	global_store_short v[32:33], v63, off
	v_cmp_lt_i32_e32 vcc, s4, v55
	v_mov_b32_e32 v32, 0
	s_and_saveexec_b64 s[4:5], vcc
	s_cbranch_execz .LBB0_783
	v_mad_i64_i32 v[32:33], s[14:15], v30, s26, v[34:35]
	v_mov_b32_e32 v32, v191
	s_mov_b32 s10, 0x3f200000
	s_waitcnt vmcnt(0)
	v_lshlrev_b32_e32 v32, 16, v32
	v_mul_f32_e32 v33, 0x3d372713, v32
	v_mul_f32_e32 v33, v33, v32
	v_fma_f32 v33, v33, v32, v32
	v_mul_f32_e32 v33, 0x3f4c422a, v33
	v_cmp_nlt_f32_e64 s[14:15], |v33|, s10
	s_and_saveexec_b64 s[28:29], s[14:15]
	s_xor_b64 s[14:15], exec, s[28:29]
	s_cbranch_execz .LBB0_780
	v_add_f32_e64 v62, |v33|, |v33|
	v_mul_f32_e32 v63, 0x3fb8aa3b, v62
	v_rndne_f32_e32 v64, v63
	s_mov_b32 s10, 0x3fb8aa3b
	v_sub_f32_e32 v65, v63, v64
	v_fma_f32 v63, v62, s10, -v63
	v_fmac_f32_e32 v63, 0x32a5705f, v62
	v_add_f32_e32 v63, v65, v63
	v_cvt_i32_f32_e32 v64, v64
	v_exp_f32_e32 v63, v63
	s_mov_b32 s10, 0xc2ce8ed0
	v_cmp_ngt_f32_e32 vcc, s10, v62
	s_mov_b32 s10, 0x42b17218
	v_ldexp_f32 v63, v63, v64
	v_cndmask_b32_e32 v63, 0, v63, vcc
	v_cmp_nlt_f32_e32 vcc, s10, v62
	s_nop 1
	v_cndmask_b32_e32 v62, v213, v63, vcc
	v_add_f32_e32 v62, 1.0, v62
	v_rcp_f32_e32 v62, v62
	s_nop 0
	v_fma_f32 v62, v62, -2.0, 1.0

; __device__ __forceinline__ float bf2f(bf16_t b) { return __uint_as_float(((unsigned)b) << 16); }
; __device__ __forceinline__ unsigned f2bf(float f) { return pk2(f, 0.f) & 0xffffu; }
; __device__ __forceinline__ float gelu_tanh(float x) { return 0.5f * x * (1.0f + tanhf(0.7978845608028654f * (x + 0.044715f * x * x * x))); }
; __device__ __forceinline__ void lru_s3_item(CParams& p, int item, LAS unsigned char* lds) {
;     ...
;         for (int s = 0; s < 16; ++s) { const int tt = dir ? 15 - s : s; h = av[dir][tt] * h + bv[dir][tt]; if (dir == 0) hs[tt] = h; else hs[tt] += h; }
;     }
; #pragma unroll
;     for (int tt = 0; tt < 16; ++tt) { const int i = 16 * tq + tt; const bool valid = (c * 128 + i - 112) >= 0;
;         const float ga = bf2f(P[ro[tt] * NMIX + 512 + ch]);
;         Z[ro[tt] * D + ch] = (bf16_t)(valid ? f2bf(hs[tt] * gelu_tanh(ga)) : 0u); }
.LBB0_783:
	s_or_b64 exec, exec, s[4:5]
	v_lshlrev_b64 v[30:31], 12, v[30:31]
	v_lshl_add_u64 v[30:31], v[36:37], 0, v[30:31]
	global_store_short v[30:31], v32, off
	v_or_b32_e32 v30, 2, v55
	v_fmac_f32_e32 v80, v61, v81
	v_cmp_lt_i32_e32 vcc, s93, v30
	v_mov_b32_e32 v30, 0
	s_and_saveexec_b64 s[4:5], vcc
	s_cbranch_execz .LBB0_789
	v_mad_i64_i32 v[30:31], s[14:15], v28, s26, v[34:35]
	v_mov_b32_e32 v30, v192
	s_mov_b32 s10, 0x3f200000
	s_waitcnt vmcnt(0)
	v_lshlrev_b32_e32 v30, 16, v30
	v_mul_f32_e32 v31, 0x3d372713, v30
	v_mul_f32_e32 v31, v31, v30
	v_fma_f32 v31, v31, v30, v30
	v_mul_f32_e32 v31, 0x3f4c422a, v31
	v_cmp_nlt_f32_e64 s[14:15], |v31|, s10
	s_and_saveexec_b64 s[28:29], s[14:15]
	s_xor_b64 s[14:15], exec, s[28:29]
	s_cbranch_execz .LBB0_786
	v_add_f32_e64 v32, |v31|, |v31|
	v_mul_f32_e32 v33, 0x3fb8aa3b, v32
	v_rndne_f32_e32 v61, v33
	s_mov_b32 s10, 0x3fb8aa3b
	v_sub_f32_e32 v62, v33, v61
	v_fma_f32 v33, v32, s10, -v33
	v_fmac_f32_e32 v33, 0x32a5705f, v32
	v_add_f32_e32 v33, v62, v33
	v_cvt_i32_f32_e32 v61, v61
	v_exp_f32_e32 v33, v33
	s_mov_b32 s10, 0xc2ce8ed0
	v_cmp_ngt_f32_e32 vcc, s10, v32
	s_mov_b32 s10, 0x42b17218
	v_ldexp_f32 v33, v33, v61
	v_cndmask_b32_e32 v33, 0, v33, vcc
	v_cmp_nlt_f32_e32 vcc, s10, v32
	s_nop 1
	v_cndmask_b32_e32 v32, v213, v33, vcc
	v_add_f32_e32 v32, 1.0, v32
	v_rcp_f32_e32 v32, v32
	s_nop 0
	v_fma_f32 v32, v32, -2.0, 1.0

; __device__ __forceinline__ float bf2f(bf16_t b) { return __uint_as_float(((unsigned)b) << 16); }
; __device__ __forceinline__ unsigned f2bf(float f) { return pk2(f, 0.f) & 0xffffu; }
; __device__ __forceinline__ float gelu_tanh(float x) { return 0.5f * x * (1.0f + tanhf(0.7978845608028654f * (x + 0.044715f * x * x * x))); }
; __device__ __forceinline__ void lru_s3_item(CParams& p, int item, LAS unsigned char* lds) {
;     ...
;         for (int s = 0; s < 16; ++s) { const int tt = dir ? 15 - s : s; h = av[dir][tt] * h + bv[dir][tt]; if (dir == 0) hs[tt] = h; else hs[tt] += h; }
;     }
; #pragma unroll
;     for (int tt = 0; tt < 16; ++tt) { const int i = 16 * tq + tt; const bool valid = (c * 128 + i - 112) >= 0;
;         const float ga = bf2f(P[ro[tt] * NMIX + 512 + ch]);
;         Z[ro[tt] * D + ch] = (bf16_t)(valid ? f2bf(hs[tt] * gelu_tanh(ga)) : 0u); }
.LBB0_789:
	s_or_b64 exec, exec, s[4:5]
	v_lshlrev_b64 v[28:29], 12, v[28:29]
	v_lshl_add_u64 v[28:29], v[36:37], 0, v[28:29]
	global_store_short v[28:29], v30, off
	v_or_b32_e32 v28, 3, v55
	v_fmac_f32_e32 v79, v60, v80
	v_cmp_lt_i32_e32 vcc, s93, v28
	v_mov_b32_e32 v28, 0
	s_and_saveexec_b64 s[4:5], vcc
	s_cbranch_execz .LBB0_795
	v_mad_i64_i32 v[28:29], s[14:15], v26, s26, v[34:35]
	v_mov_b32_e32 v28, v193
	s_mov_b32 s10, 0x3f200000
	s_waitcnt vmcnt(0)
	v_lshlrev_b32_e32 v28, 16, v28
	v_mul_f32_e32 v29, 0x3d372713, v28
	v_mul_f32_e32 v29, v29, v28
	v_fma_f32 v29, v29, v28, v28
	v_mul_f32_e32 v29, 0x3f4c422a, v29
	v_cmp_nlt_f32_e64 s[14:15], |v29|, s10
	s_and_saveexec_b64 s[28:29], s[14:15]
	s_xor_b64 s[14:15], exec, s[28:29]
	s_cbranch_execz .LBB0_792
	v_add_f32_e64 v30, |v29|, |v29|
	v_mul_f32_e32 v31, 0x3fb8aa3b, v30
	v_rndne_f32_e32 v32, v31
	s_mov_b32 s10, 0x3fb8aa3b
	v_sub_f32_e32 v33, v31, v32
	v_fma_f32 v31, v30, s10, -v31
	v_fmac_f32_e32 v31, 0x32a5705f, v30
	v_add_f32_e32 v31, v33, v31
	v_cvt_i32_f32_e32 v32, v32
	v_exp_f32_e32 v31, v31
	s_mov_b32 s10, 0xc2ce8ed0
	v_cmp_ngt_f32_e32 vcc, s10, v30
	s_mov_b32 s10, 0x42b17218
	v_ldexp_f32 v31, v31, v32
	v_cndmask_b32_e32 v31, 0, v31, vcc
	v_cmp_nlt_f32_e32 vcc, s10, v30
	s_nop 1
	v_cndmask_b32_e32 v30, v213, v31, vcc
	v_add_f32_e32 v30, 1.0, v30
	v_rcp_f32_e32 v30, v30
	s_nop 0
	v_fma_f32 v30, v30, -2.0, 1.0

; __device__ __forceinline__ float bf2f(bf16_t b) { return __uint_as_float(((unsigned)b) << 16); }
; __device__ __forceinline__ unsigned f2bf(float f) { return pk2(f, 0.f) & 0xffffu; }
; __device__ __forceinline__ float gelu_tanh(float x) { return 0.5f * x * (1.0f + tanhf(0.7978845608028654f * (x + 0.044715f * x * x * x))); }
; __device__ __forceinline__ void lru_s3_item(CParams& p, int item, LAS unsigned char* lds) {
;     ...
;         for (int s = 0; s < 16; ++s) { const int tt = dir ? 15 - s : s; h = av[dir][tt] * h + bv[dir][tt]; if (dir == 0) hs[tt] = h; else hs[tt] += h; }
;     }
; #pragma unroll
;     for (int tt = 0; tt < 16; ++tt) { const int i = 16 * tq + tt; const bool valid = (c * 128 + i - 112) >= 0;
;         const float ga = bf2f(P[ro[tt] * NMIX + 512 + ch]);
;         Z[ro[tt] * D + ch] = (bf16_t)(valid ? f2bf(hs[tt] * gelu_tanh(ga)) : 0u); }
.LBB0_795:
	s_or_b64 exec, exec, s[4:5]
	v_lshlrev_b64 v[26:27], 12, v[26:27]
	v_lshl_add_u64 v[26:27], v[36:37], 0, v[26:27]
	global_store_short v[26:27], v28, off
	v_or_b32_e32 v26, 4, v55
	v_fmac_f32_e32 v78, v59, v79
	v_cmp_lt_i32_e32 vcc, s93, v26
	v_mov_b32_e32 v26, 0
	s_and_saveexec_b64 s[4:5], vcc
	s_cbranch_execz .LBB0_801
	v_mad_i64_i32 v[26:27], s[14:15], v24, s26, v[34:35]
	v_mov_b32_e32 v26, v194
	s_mov_b32 s10, 0x3f200000
	s_waitcnt vmcnt(0)
	v_lshlrev_b32_e32 v26, 16, v26
	v_mul_f32_e32 v27, 0x3d372713, v26
	v_mul_f32_e32 v27, v27, v26
	v_fma_f32 v27, v27, v26, v26
	v_mul_f32_e32 v27, 0x3f4c422a, v27
	v_cmp_nlt_f32_e64 s[14:15], |v27|, s10
	s_and_saveexec_b64 s[28:29], s[14:15]
	s_xor_b64 s[14:15], exec, s[28:29]
	s_cbranch_execz .LBB0_798
	v_add_f32_e64 v28, |v27|, |v27|
	v_mul_f32_e32 v29, 0x3fb8aa3b, v28
	v_rndne_f32_e32 v30, v29
	s_mov_b32 s10, 0x3fb8aa3b
	v_sub_f32_e32 v31, v29, v30
	v_fma_f32 v29, v28, s10, -v29
	v_fmac_f32_e32 v29, 0x32a5705f, v28
	v_add_f32_e32 v29, v31, v29
	v_cvt_i32_f32_e32 v30, v30
	v_exp_f32_e32 v29, v29
	s_mov_b32 s10, 0xc2ce8ed0
	v_cmp_ngt_f32_e32 vcc, s10, v28
	s_mov_b32 s10, 0x42b17218
	v_ldexp_f32 v29, v29, v30
	v_cndmask_b32_e32 v29, 0, v29, vcc
	v_cmp_nlt_f32_e32 vcc, s10, v28
	s_nop 1
	v_cndmask_b32_e32 v28, v213, v29, vcc
	v_add_f32_e32 v28, 1.0, v28
	v_rcp_f32_e32 v28, v28
	s_nop 0
	v_fma_f32 v28, v28, -2.0, 1.0

; __device__ __forceinline__ float bf2f(bf16_t b) { return __uint_as_float(((unsigned)b) << 16); }
; __device__ __forceinline__ unsigned f2bf(float f) { return pk2(f, 0.f) & 0xffffu; }
; __device__ __forceinline__ float gelu_tanh(float x) { return 0.5f * x * (1.0f + tanhf(0.7978845608028654f * (x + 0.044715f * x * x * x))); }
; __device__ __forceinline__ void lru_s3_item(CParams& p, int item, LAS unsigned char* lds) {
;     ...
;         for (int s = 0; s < 16; ++s) { const int tt = dir ? 15 - s : s; h = av[dir][tt] * h + bv[dir][tt]; if (dir == 0) hs[tt] = h; else hs[tt] += h; }
;     }
; #pragma unroll
;     for (int tt = 0; tt < 16; ++tt) { const int i = 16 * tq + tt; const bool valid = (c * 128 + i - 112) >= 0;
;         const float ga = bf2f(P[ro[tt] * NMIX + 512 + ch]);
;         Z[ro[tt] * D + ch] = (bf16_t)(valid ? f2bf(hs[tt] * gelu_tanh(ga)) : 0u); }
.LBB0_801:
	s_or_b64 exec, exec, s[4:5]
	v_lshlrev_b64 v[24:25], 12, v[24:25]
	v_lshl_add_u64 v[24:25], v[36:37], 0, v[24:25]
	global_store_short v[24:25], v26, off
	v_or_b32_e32 v24, 5, v55
	v_fmac_f32_e32 v77, v58, v78
	v_cmp_lt_i32_e32 vcc, s93, v24
	v_mov_b32_e32 v24, 0
	s_and_saveexec_b64 s[4:5], vcc
	s_cbranch_execz .LBB0_807
	v_mad_i64_i32 v[24:25], s[14:15], v22, s26, v[34:35]
	v_mov_b32_e32 v24, v195
	s_mov_b32 s10, 0x3f200000
	s_waitcnt vmcnt(0)
	v_lshlrev_b32_e32 v24, 16, v24
	v_mul_f32_e32 v25, 0x3d372713, v24
	v_mul_f32_e32 v25, v25, v24
	v_fma_f32 v25, v25, v24, v24
	v_mul_f32_e32 v25, 0x3f4c422a, v25
	v_cmp_nlt_f32_e64 s[14:15], |v25|, s10
	s_and_saveexec_b64 s[28:29], s[14:15]
	s_xor_b64 s[14:15], exec, s[28:29]
	s_cbranch_execz .LBB0_804
	v_add_f32_e64 v26, |v25|, |v25|
	v_mul_f32_e32 v27, 0x3fb8aa3b, v26
	v_rndne_f32_e32 v28, v27
	s_mov_b32 s10, 0x3fb8aa3b
	v_sub_f32_e32 v29, v27, v28
	v_fma_f32 v27, v26, s10, -v27
	v_fmac_f32_e32 v27, 0x32a5705f, v26
	v_add_f32_e32 v27, v29, v27
	v_cvt_i32_f32_e32 v28, v28
	v_exp_f32_e32 v27, v27
	s_mov_b32 s10, 0xc2ce8ed0
	v_cmp_ngt_f32_e32 vcc, s10, v26
	s_mov_b32 s10, 0x42b17218
	v_ldexp_f32 v27, v27, v28
	v_cndmask_b32_e32 v27, 0, v27, vcc
	v_cmp_nlt_f32_e32 vcc, s10, v26
	s_nop 1
	v_cndmask_b32_e32 v26, v213, v27, vcc
	v_add_f32_e32 v26, 1.0, v26
	v_rcp_f32_e32 v26, v26
	s_nop 0
	v_fma_f32 v26, v26, -2.0, 1.0

; __device__ __forceinline__ float bf2f(bf16_t b) { return __uint_as_float(((unsigned)b) << 16); }
; __device__ __forceinline__ unsigned f2bf(float f) { return pk2(f, 0.f) & 0xffffu; }
; __device__ __forceinline__ float gelu_tanh(float x) { return 0.5f * x * (1.0f + tanhf(0.7978845608028654f * (x + 0.044715f * x * x * x))); }
; __device__ __forceinline__ void lru_s3_item(CParams& p, int item, LAS unsigned char* lds) {
;     ...
;         for (int s = 0; s < 16; ++s) { const int tt = dir ? 15 - s : s; h = av[dir][tt] * h + bv[dir][tt]; if (dir == 0) hs[tt] = h; else hs[tt] += h; }
;     }
; #pragma unroll
;     for (int tt = 0; tt < 16; ++tt) { const int i = 16 * tq + tt; const bool valid = (c * 128 + i - 112) >= 0;
;         const float ga = bf2f(P[ro[tt] * NMIX + 512 + ch]);
;         Z[ro[tt] * D + ch] = (bf16_t)(valid ? f2bf(hs[tt] * gelu_tanh(ga)) : 0u); }
.LBB0_807:
	s_or_b64 exec, exec, s[4:5]
	v_lshlrev_b64 v[22:23], 12, v[22:23]
	v_lshl_add_u64 v[22:23], v[36:37], 0, v[22:23]
	global_store_short v[22:23], v24, off
	v_or_b32_e32 v22, 6, v55
	v_fmac_f32_e32 v76, v57, v77
	v_cmp_lt_i32_e32 vcc, s93, v22
	v_mov_b32_e32 v22, 0
	s_and_saveexec_b64 s[4:5], vcc
	s_cbranch_execz .LBB0_813
	v_mad_i64_i32 v[22:23], s[14:15], v20, s26, v[34:35]
	v_mov_b32_e32 v22, v196
	s_mov_b32 s10, 0x3f200000
	s_waitcnt vmcnt(0)
	v_lshlrev_b32_e32 v22, 16, v22
	v_mul_f32_e32 v23, 0x3d372713, v22
	v_mul_f32_e32 v23, v23, v22
	v_fma_f32 v23, v23, v22, v22
	v_mul_f32_e32 v23, 0x3f4c422a, v23
	v_cmp_nlt_f32_e64 s[14:15], |v23|, s10
	s_and_saveexec_b64 s[28:29], s[14:15]
	s_xor_b64 s[14:15], exec, s[28:29]
	s_cbranch_execz .LBB0_810
	v_add_f32_e64 v24, |v23|, |v23|
	v_mul_f32_e32 v25, 0x3fb8aa3b, v24
	v_rndne_f32_e32 v26, v25
	s_mov_b32 s10, 0x3fb8aa3b
	v_sub_f32_e32 v27, v25, v26
	v_fma_f32 v25, v24, s10, -v25
	v_fmac_f32_e32 v25, 0x32a5705f, v24
	v_add_f32_e32 v25, v27, v25
	v_cvt_i32_f32_e32 v26, v26
	v_exp_f32_e32 v25, v25
	s_mov_b32 s10, 0xc2ce8ed0
	v_cmp_ngt_f32_e32 vcc, s10, v24
	s_mov_b32 s10, 0x42b17218
	v_ldexp_f32 v25, v25, v26
	v_cndmask_b32_e32 v25, 0, v25, vcc
	v_cmp_nlt_f32_e32 vcc, s10, v24
	s_nop 1
	v_cndmask_b32_e32 v24, v213, v25, vcc
	v_add_f32_e32 v24, 1.0, v24
	v_rcp_f32_e32 v24, v24
	s_nop 0
	v_fma_f32 v24, v24, -2.0, 1.0

; __device__ __forceinline__ float bf2f(bf16_t b) { return __uint_as_float(((unsigned)b) << 16); }
; __device__ __forceinline__ unsigned f2bf(float f) { return pk2(f, 0.f) & 0xffffu; }
; __device__ __forceinline__ float gelu_tanh(float x) { return 0.5f * x * (1.0f + tanhf(0.7978845608028654f * (x + 0.044715f * x * x * x))); }
; __device__ __forceinline__ void lru_s3_item(CParams& p, int item, LAS unsigned char* lds) {
;     ...
;         for (int s = 0; s < 16; ++s) { const int tt = dir ? 15 - s : s; h = av[dir][tt] * h + bv[dir][tt]; if (dir == 0) hs[tt] = h; else hs[tt] += h; }
;     }
; #pragma unroll
;     for (int tt = 0; tt < 16; ++tt) { const int i = 16 * tq + tt; const bool valid = (c * 128 + i - 112) >= 0;
;         const float ga = bf2f(P[ro[tt] * NMIX + 512 + ch]);
;         Z[ro[tt] * D + ch] = (bf16_t)(valid ? f2bf(hs[tt] * gelu_tanh(ga)) : 0u); }
.LBB0_813:
	s_or_b64 exec, exec, s[4:5]
	v_lshlrev_b64 v[20:21], 12, v[20:21]
	v_lshl_add_u64 v[20:21], v[36:37], 0, v[20:21]
	global_store_short v[20:21], v22, off
	v_or_b32_e32 v20, 7, v55
	v_fmac_f32_e32 v75, v56, v76
	v_cmp_lt_i32_e32 vcc, s93, v20
	v_mov_b32_e32 v20, 0
	s_and_saveexec_b64 s[4:5], vcc
	s_cbranch_execz .LBB0_819
	v_mad_i64_i32 v[20:21], s[14:15], v18, s26, v[34:35]
	v_mov_b32_e32 v20, v197
	s_mov_b32 s10, 0x3f200000
	s_waitcnt vmcnt(0)
	v_lshlrev_b32_e32 v20, 16, v20
	v_mul_f32_e32 v21, 0x3d372713, v20
	v_mul_f32_e32 v21, v21, v20
	v_fma_f32 v21, v21, v20, v20
	v_mul_f32_e32 v21, 0x3f4c422a, v21
	v_cmp_nlt_f32_e64 s[14:15], |v21|, s10
	s_and_saveexec_b64 s[28:29], s[14:15]
	s_xor_b64 s[14:15], exec, s[28:29]
	s_cbranch_execz .LBB0_816
	v_add_f32_e64 v22, |v21|, |v21|
	v_mul_f32_e32 v23, 0x3fb8aa3b, v22
	v_rndne_f32_e32 v24, v23
	s_mov_b32 s10, 0x3fb8aa3b
	v_sub_f32_e32 v25, v23, v24
	v_fma_f32 v23, v22, s10, -v23
	v_fmac_f32_e32 v23, 0x32a5705f, v22
	v_add_f32_e32 v23, v25, v23
	v_cvt_i32_f32_e32 v24, v24
	v_exp_f32_e32 v23, v23
	s_mov_b32 s10, 0xc2ce8ed0
	v_cmp_ngt_f32_e32 vcc, s10, v22
	s_mov_b32 s10, 0x42b17218
	v_ldexp_f32 v23, v23, v24
	v_cndmask_b32_e32 v23, 0, v23, vcc
	v_cmp_nlt_f32_e32 vcc, s10, v22
	s_nop 1
	v_cndmask_b32_e32 v22, v213, v23, vcc
	v_add_f32_e32 v22, 1.0, v22
	v_rcp_f32_e32 v22, v22
	s_nop 0
	v_fma_f32 v22, v22, -2.0, 1.0

; __device__ __forceinline__ float bf2f(bf16_t b) { return __uint_as_float(((unsigned)b) << 16); }
; __device__ __forceinline__ unsigned f2bf(float f) { return pk2(f, 0.f) & 0xffffu; }
; __device__ __forceinline__ float gelu_tanh(float x) { return 0.5f * x * (1.0f + tanhf(0.7978845608028654f * (x + 0.044715f * x * x * x))); }
; __device__ __forceinline__ void lru_s3_item(CParams& p, int item, LAS unsigned char* lds) {
;     ...
;         for (int s = 0; s < 16; ++s) { const int tt = dir ? 15 - s : s; h = av[dir][tt] * h + bv[dir][tt]; if (dir == 0) hs[tt] = h; else hs[tt] += h; }
;     }
; #pragma unroll
;     for (int tt = 0; tt < 16; ++tt) { const int i = 16 * tq + tt; const bool valid = (c * 128 + i - 112) >= 0;
;         const float ga = bf2f(P[ro[tt] * NMIX + 512 + ch]);
;         Z[ro[tt] * D + ch] = (bf16_t)(valid ? f2bf(hs[tt] * gelu_tanh(ga)) : 0u); }
.LBB0_819:
	s_or_b64 exec, exec, s[4:5]
	v_lshlrev_b64 v[18:19], 12, v[18:19]
	v_lshl_add_u64 v[18:19], v[36:37], 0, v[18:19]
	global_store_short v[18:19], v20, off
	v_or_b32_e32 v18, 8, v55
	v_fmac_f32_e32 v74, v54, v75
	v_cmp_lt_i32_e32 vcc, s93, v18
	v_mov_b32_e32 v18, 0
	s_and_saveexec_b64 s[4:5], vcc
	s_cbranch_execz .LBB0_825
	v_mad_i64_i32 v[18:19], s[14:15], v16, s26, v[34:35]
	v_mov_b32_e32 v18, v198
	s_mov_b32 s10, 0x3f200000
	s_waitcnt vmcnt(0)
	v_lshlrev_b32_e32 v18, 16, v18
	v_mul_f32_e32 v19, 0x3d372713, v18
	v_mul_f32_e32 v19, v19, v18
	v_fma_f32 v19, v19, v18, v18
	v_mul_f32_e32 v19, 0x3f4c422a, v19
	v_cmp_nlt_f32_e64 s[14:15], |v19|, s10
	s_and_saveexec_b64 s[28:29], s[14:15]
	s_xor_b64 s[14:15], exec, s[28:29]
	s_cbranch_execz .LBB0_822
	v_add_f32_e64 v20, |v19|, |v19|
	v_mul_f32_e32 v21, 0x3fb8aa3b, v20
	v_rndne_f32_e32 v22, v21
	s_mov_b32 s10, 0x3fb8aa3b
	v_sub_f32_e32 v23, v21, v22
	v_fma_f32 v21, v20, s10, -v21
	v_fmac_f32_e32 v21, 0x32a5705f, v20
	v_add_f32_e32 v21, v23, v21
	v_cvt_i32_f32_e32 v22, v22
	v_exp_f32_e32 v21, v21
	s_mov_b32 s10, 0xc2ce8ed0
	v_cmp_ngt_f32_e32 vcc, s10, v20
	s_mov_b32 s10, 0x42b17218
	v_ldexp_f32 v21, v21, v22
	v_cndmask_b32_e32 v21, 0, v21, vcc
	v_cmp_nlt_f32_e32 vcc, s10, v20
	s_nop 1
	v_cndmask_b32_e32 v20, v213, v21, vcc
	v_add_f32_e32 v20, 1.0, v20
	v_rcp_f32_e32 v20, v20
	s_nop 0
	v_fma_f32 v20, v20, -2.0, 1.0

; __device__ __forceinline__ float bf2f(bf16_t b) { return __uint_as_float(((unsigned)b) << 16); }
; __device__ __forceinline__ unsigned f2bf(float f) { return pk2(f, 0.f) & 0xffffu; }
; __device__ __forceinline__ float gelu_tanh(float x) { return 0.5f * x * (1.0f + tanhf(0.7978845608028654f * (x + 0.044715f * x * x * x))); }
; __device__ __forceinline__ void lru_s3_item(CParams& p, int item, LAS unsigned char* lds) {
;     ...
;         for (int s = 0; s < 16; ++s) { const int tt = dir ? 15 - s : s; h = av[dir][tt] * h + bv[dir][tt]; if (dir == 0) hs[tt] = h; else hs[tt] += h; }
;     }
; #pragma unroll
;     for (int tt = 0; tt < 16; ++tt) { const int i = 16 * tq + tt; const bool valid = (c * 128 + i - 112) >= 0;
;         const float ga = bf2f(P[ro[tt] * NMIX + 512 + ch]);
;         Z[ro[tt] * D + ch] = (bf16_t)(valid ? f2bf(hs[tt] * gelu_tanh(ga)) : 0u); }
.LBB0_825:
	s_or_b64 exec, exec, s[4:5]
	v_lshlrev_b64 v[16:17], 12, v[16:17]
	v_lshl_add_u64 v[16:17], v[36:37], 0, v[16:17]
	global_store_short v[16:17], v18, off
	v_or_b32_e32 v16, 9, v55
	v_fmac_f32_e32 v73, v53, v74
	v_cmp_lt_i32_e32 vcc, s93, v16
	v_mov_b32_e32 v16, 0
	s_and_saveexec_b64 s[4:5], vcc
	s_cbranch_execz .LBB0_831
	v_mad_i64_i32 v[16:17], s[14:15], v14, s26, v[34:35]
	v_mov_b32_e32 v16, v199
	s_mov_b32 s10, 0x3f200000
	s_waitcnt vmcnt(0)
	v_lshlrev_b32_e32 v16, 16, v16
	v_mul_f32_e32 v17, 0x3d372713, v16
	v_mul_f32_e32 v17, v17, v16
	v_fma_f32 v17, v17, v16, v16
	v_mul_f32_e32 v17, 0x3f4c422a, v17
	v_cmp_nlt_f32_e64 s[14:15], |v17|, s10
	s_and_saveexec_b64 s[28:29], s[14:15]
	s_xor_b64 s[14:15], exec, s[28:29]
	s_cbranch_execz .LBB0_828
	v_add_f32_e64 v18, |v17|, |v17|
	v_mul_f32_e32 v19, 0x3fb8aa3b, v18
	v_rndne_f32_e32 v20, v19
	s_mov_b32 s10, 0x3fb8aa3b
	v_sub_f32_e32 v21, v19, v20
	v_fma_f32 v19, v18, s10, -v19
	v_fmac_f32_e32 v19, 0x32a5705f, v18
	v_add_f32_e32 v19, v21, v19
	v_cvt_i32_f32_e32 v20, v20
	v_exp_f32_e32 v19, v19
	s_mov_b32 s10, 0xc2ce8ed0
	v_cmp_ngt_f32_e32 vcc, s10, v18
	s_mov_b32 s10, 0x42b17218
	v_ldexp_f32 v19, v19, v20
	v_cndmask_b32_e32 v19, 0, v19, vcc
	v_cmp_nlt_f32_e32 vcc, s10, v18
	s_nop 1
	v_cndmask_b32_e32 v18, v213, v19, vcc
	v_add_f32_e32 v18, 1.0, v18
	v_rcp_f32_e32 v18, v18
	s_nop 0
	v_fma_f32 v18, v18, -2.0, 1.0

; __device__ __forceinline__ float bf2f(bf16_t b) { return __uint_as_float(((unsigned)b) << 16); }
; __device__ __forceinline__ unsigned f2bf(float f) { return pk2(f, 0.f) & 0xffffu; }
; __device__ __forceinline__ float gelu_tanh(float x) { return 0.5f * x * (1.0f + tanhf(0.7978845608028654f * (x + 0.044715f * x * x * x))); }
; __device__ __forceinline__ void lru_s3_item(CParams& p, int item, LAS unsigned char* lds) {
;     ...
;         for (int s = 0; s < 16; ++s) { const int tt = dir ? 15 - s : s; h = av[dir][tt] * h + bv[dir][tt]; if (dir == 0) hs[tt] = h; else hs[tt] += h; }
;     }
; #pragma unroll
;     for (int tt = 0; tt < 16; ++tt) { const int i = 16 * tq + tt; const bool valid = (c * 128 + i - 112) >= 0;
;         const float ga = bf2f(P[ro[tt] * NMIX + 512 + ch]);
;         Z[ro[tt] * D + ch] = (bf16_t)(valid ? f2bf(hs[tt] * gelu_tanh(ga)) : 0u); }
.LBB0_831:
	s_or_b64 exec, exec, s[4:5]
	v_lshlrev_b64 v[14:15], 12, v[14:15]
	v_lshl_add_u64 v[14:15], v[36:37], 0, v[14:15]
	global_store_short v[14:15], v16, off
	v_or_b32_e32 v14, 10, v55
	v_fmac_f32_e32 v72, v52, v73
	v_cmp_lt_i32_e32 vcc, s93, v14
	v_mov_b32_e32 v14, 0
	s_and_saveexec_b64 s[4:5], vcc
	s_cbranch_execz .LBB0_837
	v_mad_i64_i32 v[14:15], s[14:15], v12, s26, v[34:35]
	v_mov_b32_e32 v14, v200
	s_mov_b32 s10, 0x3f200000
	s_waitcnt vmcnt(0)
	v_lshlrev_b32_e32 v14, 16, v14
	v_mul_f32_e32 v15, 0x3d372713, v14
	v_mul_f32_e32 v15, v15, v14
	v_fma_f32 v15, v15, v14, v14
	v_mul_f32_e32 v15, 0x3f4c422a, v15
	v_cmp_nlt_f32_e64 s[14:15], |v15|, s10
	s_and_saveexec_b64 s[28:29], s[14:15]
	s_xor_b64 s[14:15], exec, s[28:29]
	s_cbranch_execz .LBB0_834
	v_add_f32_e64 v16, |v15|, |v15|
	v_mul_f32_e32 v17, 0x3fb8aa3b, v16
	v_rndne_f32_e32 v18, v17
	s_mov_b32 s10, 0x3fb8aa3b
	v_sub_f32_e32 v19, v17, v18
	v_fma_f32 v17, v16, s10, -v17
	v_fmac_f32_e32 v17, 0x32a5705f, v16
	v_add_f32_e32 v17, v19, v17
	v_cvt_i32_f32_e32 v18, v18
	v_exp_f32_e32 v17, v17
	s_mov_b32 s10, 0xc2ce8ed0
	v_cmp_ngt_f32_e32 vcc, s10, v16
	s_mov_b32 s10, 0x42b17218
	v_ldexp_f32 v17, v17, v18
	v_cndmask_b32_e32 v17, 0, v17, vcc
	v_cmp_nlt_f32_e32 vcc, s10, v16
	s_nop 1
	v_cndmask_b32_e32 v16, v213, v17, vcc
	v_add_f32_e32 v16, 1.0, v16
	v_rcp_f32_e32 v16, v16
	s_nop 0
	v_fma_f32 v16, v16, -2.0, 1.0

; __device__ __forceinline__ float bf2f(bf16_t b) { return __uint_as_float(((unsigned)b) << 16); }
; __device__ __forceinline__ unsigned f2bf(float f) { return pk2(f, 0.f) & 0xffffu; }
; __device__ __forceinline__ float gelu_tanh(float x) { return 0.5f * x * (1.0f + tanhf(0.7978845608028654f * (x + 0.044715f * x * x * x))); }
; __device__ __forceinline__ void lru_s3_item(CParams& p, int item, LAS unsigned char* lds) {
;     ...
;         for (int s = 0; s < 16; ++s) { const int tt = dir ? 15 - s : s; h = av[dir][tt] * h + bv[dir][tt]; if (dir == 0) hs[tt] = h; else hs[tt] += h; }
;     }
; #pragma unroll
;     for (int tt = 0; tt < 16; ++tt) { const int i = 16 * tq + tt; const bool valid = (c * 128 + i - 112) >= 0;
;         const float ga = bf2f(P[ro[tt] * NMIX + 512 + ch]);
;         Z[ro[tt] * D + ch] = (bf16_t)(valid ? f2bf(hs[tt] * gelu_tanh(ga)) : 0u); }
.LBB0_837:
	s_or_b64 exec, exec, s[4:5]
	v_lshlrev_b64 v[12:13], 12, v[12:13]
	v_lshl_add_u64 v[12:13], v[36:37], 0, v[12:13]
	global_store_short v[12:13], v14, off
	v_or_b32_e32 v12, 11, v55
	v_fmac_f32_e32 v71, v51, v72
	v_cmp_lt_i32_e32 vcc, s93, v12
	v_mov_b32_e32 v12, 0
	s_and_saveexec_b64 s[4:5], vcc
	s_cbranch_execz .LBB0_843
	v_mad_i64_i32 v[12:13], s[14:15], v10, s26, v[34:35]
	v_mov_b32_e32 v12, v201
	s_mov_b32 s10, 0x3f200000
	s_waitcnt vmcnt(0)
	v_lshlrev_b32_e32 v12, 16, v12
	v_mul_f32_e32 v13, 0x3d372713, v12
	v_mul_f32_e32 v13, v13, v12
	v_fma_f32 v13, v13, v12, v12
	v_mul_f32_e32 v13, 0x3f4c422a, v13
	v_cmp_nlt_f32_e64 s[14:15], |v13|, s10
	s_and_saveexec_b64 s[28:29], s[14:15]
	s_xor_b64 s[14:15], exec, s[28:29]
	s_cbranch_execz .LBB0_840
	v_add_f32_e64 v14, |v13|, |v13|
	v_mul_f32_e32 v15, 0x3fb8aa3b, v14
	v_rndne_f32_e32 v16, v15
	s_mov_b32 s10, 0x3fb8aa3b
	v_sub_f32_e32 v17, v15, v16
	v_fma_f32 v15, v14, s10, -v15
	v_fmac_f32_e32 v15, 0x32a5705f, v14
	v_add_f32_e32 v15, v17, v15
	v_cvt_i32_f32_e32 v16, v16
	v_exp_f32_e32 v15, v15
	s_mov_b32 s10, 0xc2ce8ed0
	v_cmp_ngt_f32_e32 vcc, s10, v14
	s_mov_b32 s10, 0x42b17218
	v_ldexp_f32 v15, v15, v16
	v_cndmask_b32_e32 v15, 0, v15, vcc
	v_cmp_nlt_f32_e32 vcc, s10, v14
	s_nop 1
	v_cndmask_b32_e32 v14, v213, v15, vcc
	v_add_f32_e32 v14, 1.0, v14
	v_rcp_f32_e32 v14, v14
	s_nop 0
	v_fma_f32 v14, v14, -2.0, 1.0

; __device__ __forceinline__ float bf2f(bf16_t b) { return __uint_as_float(((unsigned)b) << 16); }
; __device__ __forceinline__ unsigned f2bf(float f) { return pk2(f, 0.f) & 0xffffu; }
; __device__ __forceinline__ float gelu_tanh(float x) { return 0.5f * x * (1.0f + tanhf(0.7978845608028654f * (x + 0.044715f * x * x * x))); }
; __device__ __forceinline__ void lru_s3_item(CParams& p, int item, LAS unsigned char* lds) {
;     ...
;         for (int s = 0; s < 16; ++s) { const int tt = dir ? 15 - s : s; h = av[dir][tt] * h + bv[dir][tt]; if (dir == 0) hs[tt] = h; else hs[tt] += h; }
;     }
; #pragma unroll
;     for (int tt = 0; tt < 16; ++tt) { const int i = 16 * tq + tt; const bool valid = (c * 128 + i - 112) >= 0;
;         const float ga = bf2f(P[ro[tt] * NMIX + 512 + ch]);
;         Z[ro[tt] * D + ch] = (bf16_t)(valid ? f2bf(hs[tt] * gelu_tanh(ga)) : 0u); }
.LBB0_843:
	s_or_b64 exec, exec, s[4:5]
	v_lshlrev_b64 v[10:11], 12, v[10:11]
	v_lshl_add_u64 v[10:11], v[36:37], 0, v[10:11]
	global_store_short v[10:11], v12, off
	v_or_b32_e32 v10, 12, v55
	v_fmac_f32_e32 v70, v50, v71
	v_cmp_lt_i32_e32 vcc, s93, v10
	v_mov_b32_e32 v10, 0
	s_and_saveexec_b64 s[4:5], vcc
	s_cbranch_execz .LBB0_849
	v_mad_i64_i32 v[10:11], s[14:15], v8, s26, v[34:35]
	v_mov_b32_e32 v10, v202
	s_mov_b32 s10, 0x3f200000
	s_waitcnt vmcnt(0)
	v_lshlrev_b32_e32 v10, 16, v10
	v_mul_f32_e32 v11, 0x3d372713, v10
	v_mul_f32_e32 v11, v11, v10
	v_fma_f32 v11, v11, v10, v10
	v_mul_f32_e32 v11, 0x3f4c422a, v11
	v_cmp_nlt_f32_e64 s[14:15], |v11|, s10
	s_and_saveexec_b64 s[28:29], s[14:15]
	s_xor_b64 s[14:15], exec, s[28:29]
	s_cbranch_execz .LBB0_846
	v_add_f32_e64 v12, |v11|, |v11|
	v_mul_f32_e32 v13, 0x3fb8aa3b, v12
	v_rndne_f32_e32 v14, v13
	s_mov_b32 s10, 0x3fb8aa3b
	v_sub_f32_e32 v15, v13, v14
	v_fma_f32 v13, v12, s10, -v13
	v_fmac_f32_e32 v13, 0x32a5705f, v12
	v_add_f32_e32 v13, v15, v13
	v_cvt_i32_f32_e32 v14, v14
	v_exp_f32_e32 v13, v13
	s_mov_b32 s10, 0xc2ce8ed0
	v_cmp_ngt_f32_e32 vcc, s10, v12
	s_mov_b32 s10, 0x42b17218
	v_ldexp_f32 v13, v13, v14
	v_cndmask_b32_e32 v13, 0, v13, vcc
	v_cmp_nlt_f32_e32 vcc, s10, v12
	s_nop 1
	v_cndmask_b32_e32 v12, v213, v13, vcc
	v_add_f32_e32 v12, 1.0, v12
	v_rcp_f32_e32 v12, v12
	s_nop 0
	v_fma_f32 v12, v12, -2.0, 1.0

; __device__ __forceinline__ float bf2f(bf16_t b) { return __uint_as_float(((unsigned)b) << 16); }
; __device__ __forceinline__ unsigned f2bf(float f) { return pk2(f, 0.f) & 0xffffu; }
; __device__ __forceinline__ float gelu_tanh(float x) { return 0.5f * x * (1.0f + tanhf(0.7978845608028654f * (x + 0.044715f * x * x * x))); }
; __device__ __forceinline__ void lru_s3_item(CParams& p, int item, LAS unsigned char* lds) {
;     ...
;         for (int s = 0; s < 16; ++s) { const int tt = dir ? 15 - s : s; h = av[dir][tt] * h + bv[dir][tt]; if (dir == 0) hs[tt] = h; else hs[tt] += h; }
;     }
; #pragma unroll
;     for (int tt = 0; tt < 16; ++tt) { const int i = 16 * tq + tt; const bool valid = (c * 128 + i - 112) >= 0;
;         const float ga = bf2f(P[ro[tt] * NMIX + 512 + ch]);
;         Z[ro[tt] * D + ch] = (bf16_t)(valid ? f2bf(hs[tt] * gelu_tanh(ga)) : 0u); }
.LBB0_849:
	s_or_b64 exec, exec, s[4:5]
	v_lshlrev_b64 v[8:9], 12, v[8:9]
	v_lshl_add_u64 v[8:9], v[36:37], 0, v[8:9]
	global_store_short v[8:9], v10, off
	v_or_b32_e32 v8, 13, v55
	v_fmac_f32_e32 v69, v49, v70
	v_cmp_lt_i32_e32 vcc, s93, v8
	v_mov_b32_e32 v8, 0
	s_and_saveexec_b64 s[4:5], vcc
	s_cbranch_execz .LBB0_855
	v_mad_i64_i32 v[8:9], s[14:15], v6, s26, v[34:35]
	v_mov_b32_e32 v8, v203
	s_mov_b32 s10, 0x3f200000
	s_waitcnt vmcnt(0)
	v_lshlrev_b32_e32 v8, 16, v8
	v_mul_f32_e32 v9, 0x3d372713, v8
	v_mul_f32_e32 v9, v9, v8
	v_fma_f32 v9, v9, v8, v8
	v_mul_f32_e32 v9, 0x3f4c422a, v9
	v_cmp_nlt_f32_e64 s[14:15], |v9|, s10
	s_and_saveexec_b64 s[28:29], s[14:15]
	s_xor_b64 s[14:15], exec, s[28:29]
	s_cbranch_execz .LBB0_852
	v_add_f32_e64 v10, |v9|, |v9|
	v_mul_f32_e32 v11, 0x3fb8aa3b, v10
	v_rndne_f32_e32 v12, v11
	s_mov_b32 s10, 0x3fb8aa3b
	v_sub_f32_e32 v13, v11, v12
	v_fma_f32 v11, v10, s10, -v11
	v_fmac_f32_e32 v11, 0x32a5705f, v10
	v_add_f32_e32 v11, v13, v11
	v_cvt_i32_f32_e32 v12, v12
	v_exp_f32_e32 v11, v11
	s_mov_b32 s10, 0xc2ce8ed0
	v_cmp_ngt_f32_e32 vcc, s10, v10
	s_mov_b32 s10, 0x42b17218
	v_ldexp_f32 v11, v11, v12
	v_cndmask_b32_e32 v11, 0, v11, vcc
	v_cmp_nlt_f32_e32 vcc, s10, v10
	s_nop 1
	v_cndmask_b32_e32 v10, v213, v11, vcc
	v_add_f32_e32 v10, 1.0, v10
	v_rcp_f32_e32 v10, v10
	s_nop 0
	v_fma_f32 v10, v10, -2.0, 1.0

; __device__ __forceinline__ float bf2f(bf16_t b) { return __uint_as_float(((unsigned)b) << 16); }
; __device__ __forceinline__ unsigned f2bf(float f) { return pk2(f, 0.f) & 0xffffu; }
; __device__ __forceinline__ float gelu_tanh(float x) { return 0.5f * x * (1.0f + tanhf(0.7978845608028654f * (x + 0.044715f * x * x * x))); }
; __device__ __forceinline__ void lru_s3_item(CParams& p, int item, LAS unsigned char* lds) {
;     ...
;         for (int s = 0; s < 16; ++s) { const int tt = dir ? 15 - s : s; h = av[dir][tt] * h + bv[dir][tt]; if (dir == 0) hs[tt] = h; else hs[tt] += h; }
;     }
; #pragma unroll
;     for (int tt = 0; tt < 16; ++tt) { const int i = 16 * tq + tt; const bool valid = (c * 128 + i - 112) >= 0;
;         const float ga = bf2f(P[ro[tt] * NMIX + 512 + ch]);
;         Z[ro[tt] * D + ch] = (bf16_t)(valid ? f2bf(hs[tt] * gelu_tanh(ga)) : 0u); }
.LBB0_855:
	s_or_b64 exec, exec, s[4:5]
	v_lshlrev_b64 v[6:7], 12, v[6:7]
	v_lshl_add_u64 v[6:7], v[36:37], 0, v[6:7]
	global_store_short v[6:7], v8, off
	v_or_b32_e32 v6, 14, v55
	v_fmac_f32_e32 v3, v48, v69
	v_cmp_lt_i32_e32 vcc, s93, v6
	v_mov_b32_e32 v6, 0
	s_and_saveexec_b64 s[4:5], vcc
	s_cbranch_execz .LBB0_861
	v_mad_i64_i32 v[6:7], s[14:15], v4, s26, v[34:35]
	v_mov_b32_e32 v6, v204
	s_mov_b32 s10, 0x3f200000
	s_waitcnt vmcnt(0)
	v_lshlrev_b32_e32 v6, 16, v6
	v_mul_f32_e32 v7, 0x3d372713, v6
	v_mul_f32_e32 v7, v7, v6
	v_fma_f32 v7, v7, v6, v6
	v_mul_f32_e32 v7, 0x3f4c422a, v7
	v_cmp_nlt_f32_e64 s[14:15], |v7|, s10
	s_and_saveexec_b64 s[28:29], s[14:15]
	s_xor_b64 s[14:15], exec, s[28:29]
	s_cbranch_execz .LBB0_858
	v_add_f32_e64 v8, |v7|, |v7|
	v_mul_f32_e32 v9, 0x3fb8aa3b, v8
	v_rndne_f32_e32 v10, v9
	s_mov_b32 s10, 0x3fb8aa3b
	v_sub_f32_e32 v11, v9, v10
	v_fma_f32 v9, v8, s10, -v9
	v_fmac_f32_e32 v9, 0x32a5705f, v8
	v_add_f32_e32 v9, v11, v9
	v_cvt_i32_f32_e32 v10, v10
	v_exp_f32_e32 v9, v9
	s_mov_b32 s10, 0xc2ce8ed0
	v_cmp_ngt_f32_e32 vcc, s10, v8
	s_mov_b32 s10, 0x42b17218
	v_ldexp_f32 v9, v9, v10
	v_cndmask_b32_e32 v9, 0, v9, vcc
	v_cmp_nlt_f32_e32 vcc, s10, v8
	s_nop 1
	v_cndmask_b32_e32 v8, v213, v9, vcc
	v_add_f32_e32 v8, 1.0, v8
	v_rcp_f32_e32 v8, v8
	s_nop 0
	v_fma_f32 v8, v8, -2.0, 1.0

; __device__ __forceinline__ float bf2f(bf16_t b) { return __uint_as_float(((unsigned)b) << 16); }
; __device__ __forceinline__ unsigned f2bf(float f) { return pk2(f, 0.f) & 0xffffu; }
; __device__ __forceinline__ float gelu_tanh(float x) { return 0.5f * x * (1.0f + tanhf(0.7978845608028654f * (x + 0.044715f * x * x * x))); }
; __device__ __forceinline__ void lru_s3_item(CParams& p, int item, LAS unsigned char* lds) {
;     ...
;     for (int tt = 0; tt < 16; ++tt) { const int i = 16 * tq + tt; const bool valid = (c * 128 + i - 112) >= 0;
;         const float ga = bf2f(P[ro[tt] * NMIX + 512 + ch]);
;         Z[ro[tt] * D + ch] = (bf16_t)(valid ? f2bf(hs[tt] * gelu_tanh(ga)) : 0u); }
.LBB0_861:
	s_or_b64 exec, exec, s[4:5]
	v_lshlrev_b64 v[4:5], 12, v[4:5]
	v_lshl_add_u64 v[4:5], v[36:37], 0, v[4:5]
	global_store_short v[4:5], v6, off
	v_or_b32_e32 v4, 15, v55
	v_cmp_lt_i32_e32 vcc, s93, v4
	v_mov_b32_e32 v4, 0
	s_and_saveexec_b64 s[4:5], vcc
	s_cbranch_execz .LBB0_754
	v_mad_i64_i32 v[4:5], s[14:15], v0, s26, v[34:35]
	v_mov_b32_e32 v4, v205
	s_mov_b32 s10, 0x3f200000
	s_waitcnt vmcnt(0)
	v_lshlrev_b32_e32 v4, 16, v4
	v_mul_f32_e32 v5, 0x3d372713, v4
	v_mul_f32_e32 v5, v5, v4
	v_fma_f32 v5, v5, v4, v4
	v_mul_f32_e32 v5, 0x3f4c422a, v5
	v_cmp_nlt_f32_e64 s[14:15], |v5|, s10
	s_and_saveexec_b64 s[28:29], s[14:15]
	s_xor_b64 s[14:15], exec, s[28:29]
	s_cbranch_execz .LBB0_864
	v_add_f32_e64 v6, |v5|, |v5|
	v_mul_f32_e32 v7, 0x3fb8aa3b, v6
	v_rndne_f32_e32 v8, v7
	s_mov_b32 s10, 0x3fb8aa3b
	v_sub_f32_e32 v9, v7, v8
	v_fma_f32 v7, v6, s10, -v7
	v_fmac_f32_e32 v7, 0x32a5705f, v6
	v_add_f32_e32 v7, v9, v7
	v_cvt_i32_f32_e32 v8, v8
	v_exp_f32_e32 v7, v7
	s_mov_b32 s10, 0xc2ce8ed0
	v_cmp_ngt_f32_e32 vcc, s10, v6
	s_mov_b32 s10, 0x42b17218
	v_ldexp_f32 v7, v7, v8
	v_cndmask_b32_e32 v7, 0, v7, vcc
	v_cmp_nlt_f32_e32 vcc, s10, v6
	s_nop 1
	v_cndmask_b32_e32 v6, v213, v7, vcc
	v_add_f32_e32 v6, 1.0, v6
	v_rcp_f32_e32 v6, v6
	s_nop 0
	v_fma_f32 v6, v6, -2.0, 1.0
